# attention prologue: Q wait folded into first counted wait, accumulator zeroing after first DMAs; otherwise as previous (pipelined attention, hand SSM scans, P5 epilogue)
# speedup vs baseline: 1.0943x; 1.0001x over previous
.LBB0_209:
	s_bfe_u32 s14, s77, 0x30005
	s_lshl_b32 s15, s14, 22
	s_add_u32 s18, s31, s15
	s_addc_u32 s19, s34, 0
	s_and_b32 s12, s77, 7
	s_xor_b32 s22, s12, 15
	s_cmpk_lt_u32 s77, 0x100
	v_mov_b32_e32 v74, v165
	s_cselect_b32 s22, s12, s22
	s_bfe_u32 s24, s77, 0x20003
	v_readfirstlane_b32 s12, v74
	s_ashr_i32 s25, s12, 6
	s_lshl_b32 s29, s25, 3
	s_lshl_b32 s23, s25, 1
	s_or_b32 s53, s29, 4
	s_lshl_b32 s27, s14, 12
	s_lshl_b32 s26, s22, 2
	s_ashr_i32 s39, s12, 7
	s_lshl_b32 s12, s24, 8
	s_and_b32 s38, s23, 2
	s_bfe_u32 s54, s53, 0x20002
	s_lshl_b32 s55, s22, 8
	s_lshl_b32 s28, s14, 21
	s_add_u32 s22, s78, s15
	s_addc_u32 s23, s79, 0
	s_lshl_b32 s15, s25, 5
	s_or_b32 s14, s55, s27
	s_ashr_i32 s27, s15, 31
	s_add_u32 s14, s15, s14
	v_and_b32_e32 v168, 31, v74
	s_addc_u32 s15, s27, 0
	v_or_b32_e32 v0, s14, v168
	v_mov_b32_e32 v1, s15
	v_lshlrev_b64 v[0:1], 10, v[0:1]
	v_bfe_u32 v183, v74, 5, 1
	v_lshl_add_u64 v[0:1], s[46:47], 0, v[0:1]
	v_lshl_add_u64 v[0:1], v[0:1], 0, s[12:13]
	v_lshlrev_b32_e32 v166, 4, v183
	v_lshl_add_u64 v[0:1], v[0:1], 0, v[166:167]
	global_load_dwordx4 v[128:131], v[0:1], off offset:224
	global_load_dwordx4 v[132:135], v[0:1], off offset:192
	global_load_dwordx4 v[144:147], v[0:1], off offset:96
	global_load_dwordx4 v[148:151], v[0:1], off offset:64
	global_load_dwordx4 v[136:139], v[0:1], off offset:160
	global_load_dwordx4 v[140:143], v[0:1], off offset:128
	global_load_dwordx4 v[152:155], v[0:1], off offset:32
	global_load_dwordx4 v[156:159], v[0:1], off
	v_lshlrev_b32_e32 v2, 2, v74
	v_bfe_u32 v0, v74, 4, 2
	v_bfe_u32 v75, v74, 2, 2
	v_and_b32_e32 v2, 12, v2
	v_or_b32_e32 v5, 8, v183
	v_or_b32_e32 v76, 2, v183
	v_or_b32_e32 v6, 10, v183
	v_or_b32_e32 v7, 4, v183
	v_or_b32_e32 v8, 12, v183
	v_or_b32_e32 v9, 6, v183
	v_or_b32_e32 v10, 14, v183
	v_and_b32_e32 v1, 15, v74
	v_lshlrev_b32_e32 v3, 2, v0
	v_lshlrev_b32_e32 v4, 8, v168
	v_bitop3_b32 v11, v2, v183, v75 bitop3:0x36
	v_bitop3_b32 v5, v2, v5, v75 bitop3:0x36
	v_bitop3_b32 v12, v2, v76, v75 bitop3:0x36
	v_bitop3_b32 v6, v2, v6, v75 bitop3:0x36
	v_bitop3_b32 v7, v2, v7, v75 bitop3:0x36
	v_bitop3_b32 v8, v2, v8, v75 bitop3:0x36
	v_bitop3_b32 v9, v2, v9, v75 bitop3:0x36
	v_bitop3_b32 v2, v2, v10, v75 bitop3:0x36
	v_lshl_or_b32 v191, v11, 4, v4
	v_lshl_or_b32 v187, v5, 4, v4
	v_lshl_or_b32 v190, v12, 4, v4
	v_lshl_or_b32 v186, v6, 4, v4
	v_lshl_or_b32 v189, v7, 4, v4
	v_lshl_or_b32 v185, v8, 4, v4
	v_lshl_or_b32 v188, v9, 4, v4
	v_lshl_or_b32 v184, v2, 4, v4
	v_or_b32_e32 v2, s29, v0
	v_bitop3_b32 v4, s38, v1, v3 bitop3:0x36
	v_lshlrev_b32_e32 v2, 10, v2
	v_or_b32_e32 v0, s53, v0
	v_lshlrev_b32_e32 v4, 4, v4
	v_bitop3_b32 v1, s54, v1, v3 bitop3:0x36
	s_lshl_b32 s56, s25, 11
	v_lshlrev_b32_e32 v0, 10, v0
	v_or3_b32 v166, v4, v2, s12
	v_lshlrev_b32_e32 v1, 4, v1
	s_or_b32 s55, s56, 0x400
	v_mov_b32_e32 v171, v167
	v_or3_b32 v170, v1, v0, s12
	s_lshl_b32 s12, s24, 7
	s_add_i32 s39, s39, s26
	s_add_i32 s38, s56, 0
	s_add_i32 s57, s55, 0
	v_lshl_add_u64 v[70:71], s[22:23], 0, v[166:167]
	v_lshl_add_u64 v[64:65], s[22:23], 0, v[170:171]
	s_add_u32 s24, s22, 0x10000
	s_mov_b32 s27, 2
	v_mov_b32_e32 v72, v167
	v_mov_b32_e32 v73, v167
	s_mov_b32 s54, 0
	s_mov_b32 vcc_hi, m0
	v_mov_b32_e32 v246, v242
	v_mov_b32_e32 v247, v243
	v_lshrrev_b32_e32 v0, 3, v74
	v_and_b32_e32 v0, 2, v0
	v_bfe_u32 v1, v74, 1, 1
	v_lshlrev_b32_e32 v3, 3, v74
	v_lshlrev_b32_e32 v4, 8, v75
	v_bitop3_b32 v5, v0, v183, v1 bitop3:0x36
	v_bitop3_b32 v0, v76, v0, v1 bitop3:0x1e
	v_and_b32_e32 v3, 8, v3
	v_lshl_or_b32 v4, v183, 10, v4
	v_lshlrev_b32_e32 v0, 4, v0
	v_or3_b32 v6, v0, v4, v3
	v_lshlrev_b32_e32 v5, 4, v5
	v_or3_b32 v7, v5, v4, v3
	v_lshlrev_b32_e32 v8, 6, v75
	v_add_u32_e32 v7, 0xc000, v7
	v_add_u32_e32 v6, 0xc800, v6
	v_mov_b32_e32 v9, v8
	v_add_u32_e32 v172, v7, v9
	v_add_u32_e32 v192, v6, v9
	v_xor_b32_e32 v9, 0x40, v8
	v_add_u32_e32 v173, v7, v9
	v_add_u32_e32 v193, v6, v9
	v_xor_b32_e32 v9, 0x80, v8
	v_add_u32_e32 v174, v7, v9
	v_add_u32_e32 v194, v6, v9
	v_xor_b32_e32 v9, 0xc0, v8
	v_add_u32_e32 v175, v7, v9
	v_add_u32_e32 v197, v6, v9
	s_or_b32 s53, s26, 2
	s_add_i32 s29, s26, 4
	s_add_i32 vcc_lo, s39, 1
	s_mov_b64 s[24:25], s[22:23]
	s_add_u32 s58, s22, 0x2000000
	s_addc_u32 s59, s23, 0
	s_mov_b32 m0, s38
	s_nop 0
	global_load_lds_dwordx4 v166, s[24:25]
	s_mov_b32 m0, s57
	s_nop 0
	global_load_lds_dwordx4 v170, s[24:25]
	s_add_u32 s24, s24, 0x10000
	s_addc_u32 s25, s25, 0
	s_add_i32 m0, s38, 0xc000
	s_nop 0
	global_load_lds_dwordx4 v166, s[58:59]
	s_add_i32 m0, s57, 0xc000
	s_nop 0
	global_load_lds_dwordx4 v170, s[58:59]
	s_add_u32 s58, s58, 0x10000
	s_addc_u32 s59, s59, 0
	s_add_i32 m0, s38, 0x4000
	s_nop 0
	global_load_lds_dwordx4 v166, s[24:25]
	s_add_i32 m0, s57, 0x4000
	s_nop 0
	global_load_lds_dwordx4 v170, s[24:25]
	s_add_u32 s24, s24, 0x10000
	s_addc_u32 s25, s25, 0
	s_mov_b32 s54, 0
	v_mov_b32_e32 v0, 0
	v_mov_b32_e32 v1, 0
	v_mov_b32_e32 v2, 0
	v_mov_b32_e32 v3, 0
	v_mov_b32_e32 v4, 0
	v_mov_b32_e32 v5, 0
	v_mov_b32_e32 v6, 0
	v_mov_b32_e32 v7, 0
	v_mov_b32_e32 v8, 0
	v_mov_b32_e32 v9, 0
	v_mov_b32_e32 v10, 0
	v_mov_b32_e32 v11, 0
	v_mov_b32_e32 v12, 0
	v_mov_b32_e32 v13, 0
	v_mov_b32_e32 v14, 0
	v_mov_b32_e32 v15, 0
	v_mov_b32_e32 v16, 0
	v_mov_b32_e32 v17, 0
	v_mov_b32_e32 v18, 0
	v_mov_b32_e32 v19, 0
	v_mov_b32_e32 v20, 0
	v_mov_b32_e32 v21, 0
	v_mov_b32_e32 v22, 0
	v_mov_b32_e32 v23, 0
	v_mov_b32_e32 v24, 0
	v_mov_b32_e32 v25, 0
	v_mov_b32_e32 v26, 0
	v_mov_b32_e32 v27, 0
	v_mov_b32_e32 v28, 0
	v_mov_b32_e32 v29, 0
	v_mov_b32_e32 v30, 0
	v_mov_b32_e32 v31, 0
	v_mov_b32_e32 v32, 0
	v_mov_b32_e32 v33, 0
	v_mov_b32_e32 v34, 0
	v_mov_b32_e32 v35, 0
	v_mov_b32_e32 v36, 0
	v_mov_b32_e32 v37, 0
	v_mov_b32_e32 v38, 0
	v_mov_b32_e32 v39, 0
	v_mov_b32_e32 v40, 0
	v_mov_b32_e32 v41, 0
	v_mov_b32_e32 v42, 0
	v_mov_b32_e32 v43, 0
	v_mov_b32_e32 v44, 0
	v_mov_b32_e32 v45, 0
	v_mov_b32_e32 v46, 0
	v_mov_b32_e32 v47, 0
	v_mov_b32_e32 v48, 0
	v_mov_b32_e32 v49, 0
	v_mov_b32_e32 v50, 0
	v_mov_b32_e32 v51, 0
	v_mov_b32_e32 v52, 0
	v_mov_b32_e32 v53, 0
	v_mov_b32_e32 v54, 0
	v_mov_b32_e32 v55, 0
	v_mov_b32_e32 v56, 0
	v_mov_b32_e32 v57, 0
	v_mov_b32_e32 v58, 0
	v_mov_b32_e32 v59, 0
	v_mov_b32_e32 v60, 0
	v_mov_b32_e32 v61, 0
	v_mov_b32_e32 v62, 0
	v_mov_b32_e32 v63, 0
	v_mov_b32_e32 v198, 0
	v_mov_b32_e32 v199, 0
	v_mov_b32_e32 v200, 0
	v_mov_b32_e32 v201, 0

.Lpa_done:
	v_pk_add_f32 v[198:199], v[198:199], v[200:201]
	s_nop 1
	v_add_f32_e32 v198, v198, v199
	ds_bpermute_b32 v200, v169, v198
	s_waitcnt lgkmcnt(0)
	v_add_f32_e32 v198, v198, v200
	v_rcp_f32_e32 v167, v198
	s_barrier
	s_mov_b64 s[24:25], s[22:23]
	s_add_u32 s58, s22, 0x2000000
	s_addc_u32 s59, s23, 0
	s_mov_b32 m0, s38
	s_nop 0
	global_load_lds_dwordx4 v166, s[24:25]
	s_mov_b32 m0, s57
	s_nop 0
	global_load_lds_dwordx4 v170, s[24:25]
	s_add_u32 s24, s24, 0x10000
	s_addc_u32 s25, s25, 0
	s_add_i32 m0, s38, 0xc000
	s_nop 0
	global_load_lds_dwordx4 v166, s[58:59]
	s_add_i32 m0, s57, 0xc000
	s_nop 0
	global_load_lds_dwordx4 v170, s[58:59]
	s_add_u32 s58, s58, 0x10000
	s_addc_u32 s59, s59, 0
	s_add_i32 m0, s38, 0x4000
	s_nop 0
	global_load_lds_dwordx4 v166, s[24:25]
	s_add_i32 m0, s57, 0x4000
	s_nop 0
	global_load_lds_dwordx4 v170, s[24:25]
	s_add_u32 s24, s24, 0x10000
	s_addc_u32 s25, s25, 0
	s_mov_b32 s54, 0
	v_mov_b32_e32 v198, 0
	v_mov_b32_e32 v199, 0
	v_mov_b32_e32 v200, 0
	v_mov_b32_e32 v201, 0
	v_mov_b32_e32 v202, 0
	v_mov_b32_e32 v203, 0
	v_mov_b32_e32 v204, 0
	v_mov_b32_e32 v205, 0
	v_mov_b32_e32 v206, 0
	v_mov_b32_e32 v207, 0
	v_mov_b32_e32 v208, 0
	v_mov_b32_e32 v209, 0
	v_mov_b32_e32 v210, 0
	v_mov_b32_e32 v211, 0
	v_mov_b32_e32 v212, 0
	v_mov_b32_e32 v213, 0
	v_mov_b32_e32 v214, 0
	v_mov_b32_e32 v215, 0
	v_mov_b32_e32 v216, 0
	v_mov_b32_e32 v217, 0
	v_mov_b32_e32 v218, 0
	v_mov_b32_e32 v219, 0
	v_mov_b32_e32 v220, 0
	v_mov_b32_e32 v221, 0
	v_mov_b32_e32 v222, 0
	v_mov_b32_e32 v223, 0
	v_mov_b32_e32 v224, 0
	v_mov_b32_e32 v225, 0
	v_mov_b32_e32 v226, 0
	v_mov_b32_e32 v227, 0
	v_mov_b32_e32 v228, 0
	v_mov_b32_e32 v229, 0
	v_mov_b32_e32 v230, 0
	v_mov_b32_e32 v231, 0
	v_mov_b32_e32 v232, 0
	v_mov_b32_e32 v233, 0
	v_mov_b32_e32 v234, 0
	v_mov_b32_e32 v235, 0
	v_mov_b32_e32 v236, 0
	v_mov_b32_e32 v237, 0
	v_mov_b32_e32 v238, 0
	v_mov_b32_e32 v239, 0
	v_mov_b32_e32 v240, 0
	v_mov_b32_e32 v241, 0
	v_mov_b32_e32 v242, 0
	v_mov_b32_e32 v243, 0
	v_mov_b32_e32 v244, 0
	v_mov_b32_e32 v245, 0
	v_mov_b32_e32 v144, 0
	v_mov_b32_e32 v145, 0
	v_mov_b32_e32 v146, 0
	v_mov_b32_e32 v147, 0
	v_mov_b32_e32 v148, 0
	v_mov_b32_e32 v149, 0
	v_mov_b32_e32 v150, 0
	v_mov_b32_e32 v151, 0
	v_mov_b32_e32 v152, 0
	v_mov_b32_e32 v153, 0
	v_mov_b32_e32 v154, 0
	v_mov_b32_e32 v155, 0
	v_mov_b32_e32 v156, 0
	v_mov_b32_e32 v157, 0
	v_mov_b32_e32 v158, 0
	v_mov_b32_e32 v159, 0
	v_mov_b32_e32 v188, 0
	v_mov_b32_e32 v189, 0
	v_mov_b32_e32 v190, 0
	v_mov_b32_e32 v191, 0
